# input-GEMM epilogue stores made agent-scope write-through (sc1) so the per-workgroup L2 writeback before the u1 count has little to flush
# speedup vs baseline: 1.0205x; 1.0205x over previous
.LBB0_792:
	v_lshl_add_u32 v174, s56, 8, v179
	v_or_b32_e32 v172, 16, v174
	v_ashrrev_i32_e32 v175, 31, v174
	v_ashrrev_i32_e32 v173, 31, v172
	v_or_b32_e32 v170, 32, v174
	v_or_b32_e32 v168, 48, v174
	v_lshl_add_u64 v[130:131], v[174:175], 4, s[76:77]
	v_lshl_add_u64 v[132:133], v[172:173], 4, s[76:77]
	v_ashrrev_i32_e32 v171, 31, v170
	v_ashrrev_i32_e32 v169, 31, v168
	v_add_u32_e32 v166, 0x80, v174
	v_add_u32_e32 v164, 0x90, v174
	global_load_dwordx4 v[186:189], v[130:131], off
	global_load_dwordx4 v[190:193], v[132:133], off
	v_lshl_add_u64 v[130:131], v[170:171], 4, s[76:77]
	v_lshl_add_u64 v[132:133], v[168:169], 4, s[76:77]
	v_ashrrev_i32_e32 v167, 31, v166
	v_ashrrev_i32_e32 v165, 31, v164
	v_add_u32_e32 v162, 0xa0, v174
	v_add_u32_e32 v160, 0xb0, v174
	global_load_dwordx4 v[194:197], v[130:131], off
	global_load_dwordx4 v[146:149], v[132:133], off
	v_lshl_add_u64 v[130:131], v[166:167], 4, s[76:77]
	v_lshl_add_u64 v[132:133], v[164:165], 4, s[76:77]
	v_ashrrev_i32_e32 v163, 31, v162
	v_ashrrev_i32_e32 v161, 31, v160
	global_load_dwordx4 v[142:145], v[130:131], off
	global_load_dwordx4 v[138:141], v[132:133], off
	v_lshl_add_u64 v[130:131], v[162:163], 4, s[76:77]
	v_lshl_add_u64 v[132:133], v[160:161], 4, s[76:77]
	global_load_dwordx4 v[134:137], v[130:131], off
	s_nop 0
	global_load_dwordx4 v[130:133], v[132:133], off
	s_cmp_lt_i32 s0, 5
	s_cselect_b64 s[52:53], -1, 0
	s_and_b64 s[4:5], s[52:53], exec
	v_readlane_b32 s4, v252, 0
	v_readlane_b32 s5, v252, 1
	s_cselect_b32 s1, s5, s73
	s_cselect_b32 s4, s4, s72
	v_mov_b32_e32 v177, s1
	s_movk_i32 s1, 0x500
	s_cselect_b32 s5, 0, -5
	v_mov_b32_e32 v176, s4
	s_cselect_b32 s4, s1, 0x840
	s_add_i32 s5, s5, s0
	s_waitcnt vmcnt(0)
	v_mov_b32_e32 v198, v187
	v_mov_b32_e32 v199, v188
	v_mov_b32_e32 v187, v189
	v_pk_add_f32 v[186:187], v[198:199], v[186:187]
	s_mov_b32 s6, 0xf800000
	v_add_f32_e32 v161, v186, v187
	v_fmamk_f32 v161, v161, 0x3a800000, v234
	v_cmp_gt_f32_e32 vcc, s6, v161
	v_mul_f32_e32 v163, 0x4f800000, v161
	v_mov_b32_e32 v186, v191
	v_cndmask_b32_e32 v161, v161, v163, vcc
	v_sqrt_f32_e32 v163, v161
	v_mov_b32_e32 v187, v192
	v_mov_b32_e32 v191, v193
	v_pk_add_f32 v[186:187], v[186:187], v[190:191]
	v_add_u32_e32 v165, -1, v163
	v_fma_f32 v167, -v165, v163, v161
	v_cmp_ge_f32_e64 s[0:1], 0, v167
	v_add_u32_e32 v167, 1, v163
	s_nop 0
	v_cndmask_b32_e64 v165, v163, v165, s[0:1]
	v_fma_f32 v163, -v167, v163, v161
	v_cmp_lt_f32_e64 s[0:1], 0, v163
	s_nop 1
	v_cndmask_b32_e64 v163, v165, v167, s[0:1]
	v_mul_f32_e32 v165, 0x37800000, v163
	v_cndmask_b32_e32 v163, v163, v165, vcc
	v_cmp_class_f32_e32 vcc, v161, v235
	s_nop 1
	v_cndmask_b32_e32 v161, v163, v161, vcc
	v_div_scale_f32 v163, s[0:1], v161, v161, 1.0
	v_rcp_f32_e32 v165, v163
	s_nop 0
	v_fma_f32 v167, -v163, v165, 1.0
	v_fmac_f32_e32 v165, v167, v165
	v_div_scale_f32 v167, vcc, 1.0, v161, 1.0
	v_mul_f32_e32 v169, v167, v165
	v_fma_f32 v171, -v163, v169, v167
	v_fmac_f32_e32 v169, v171, v165
	v_fma_f32 v163, -v163, v169, v167
	v_div_fmas_f32 v163, v163, v165, v169
	v_div_fixup_f32 v178, v163, v161, 1.0
	v_add_f32_e32 v161, v186, v187
	v_fmamk_f32 v161, v161, 0x3a800000, v234
	v_cmp_gt_f32_e32 vcc, s6, v161
	v_mul_f32_e32 v163, 0x4f800000, v161
	v_mov_b32_e32 v186, v195
	v_cndmask_b32_e32 v161, v161, v163, vcc
	v_sqrt_f32_e32 v163, v161
	v_mov_b32_e32 v187, v196
	v_mov_b32_e32 v195, v197
	v_pk_add_f32 v[186:187], v[186:187], v[194:195]
	v_add_u32_e32 v165, -1, v163
	v_fma_f32 v167, -v165, v163, v161
	v_cmp_ge_f32_e64 s[0:1], 0, v167
	v_add_u32_e32 v167, 1, v163
	v_pk_mul_f32 v[128:129], v[128:129], v[178:179] op_sel_hi:[1,0]
	v_cndmask_b32_e64 v165, v163, v165, s[0:1]
	v_fma_f32 v163, -v167, v163, v161
	v_cmp_lt_f32_e64 s[0:1], 0, v163
	v_pk_mul_f32 v[126:127], v[126:127], v[178:179] op_sel_hi:[1,0]
	v_pk_mul_f32 v[120:121], v[120:121], v[178:179] op_sel_hi:[1,0]
	v_cndmask_b32_e64 v163, v165, v167, s[0:1]
	v_mul_f32_e32 v165, 0x37800000, v163
	v_cndmask_b32_e32 v163, v163, v165, vcc
	v_cmp_class_f32_e32 vcc, v161, v235
	v_pk_mul_f32 v[118:119], v[118:119], v[178:179] op_sel_hi:[1,0]
	s_nop 0
	v_cndmask_b32_e32 v161, v163, v161, vcc
	v_div_scale_f32 v163, s[0:1], v161, v161, 1.0
	v_rcp_f32_e32 v165, v163
	s_nop 0
	v_fma_f32 v167, -v163, v165, 1.0
	v_fmac_f32_e32 v165, v167, v165
	v_div_scale_f32 v167, vcc, 1.0, v161, 1.0
	v_mul_f32_e32 v169, v167, v165
	v_fma_f32 v171, -v163, v169, v167
	v_fmac_f32_e32 v169, v171, v165
	v_fma_f32 v163, -v163, v169, v167
	v_div_fmas_f32 v163, v163, v165, v169
	v_div_fixup_f32 v180, v163, v161, 1.0
	v_add_f32_e32 v161, v186, v187
	v_fmamk_f32 v161, v161, 0x3a800000, v234
	v_cmp_gt_f32_e32 vcc, s6, v161
	v_mul_f32_e32 v163, 0x4f800000, v161
	v_mov_b32_e32 v186, v147
	v_cndmask_b32_e32 v161, v161, v163, vcc
	v_sqrt_f32_e32 v163, v161
	v_mov_b32_e32 v187, v148
	v_mov_b32_e32 v147, v149
	v_pk_add_f32 v[146:147], v[186:187], v[146:147]
	v_add_u32_e32 v165, -1, v163
	v_fma_f32 v167, -v165, v163, v161
	v_cmp_ge_f32_e64 s[0:1], 0, v167
	v_add_u32_e32 v167, 1, v163
	v_add_f32_e32 v146, v146, v147
	v_cndmask_b32_e64 v165, v163, v165, s[0:1]
	v_fma_f32 v163, -v167, v163, v161
	v_cmp_lt_f32_e64 s[0:1], 0, v163
	v_fmamk_f32 v146, v146, 0x3a800000, v234
	v_mul_f32_e32 v147, 0x4f800000, v146
	v_cndmask_b32_e64 v163, v165, v167, s[0:1]
	v_mul_f32_e32 v165, 0x37800000, v163
	v_cndmask_b32_e32 v163, v163, v165, vcc
	v_cmp_class_f32_e32 vcc, v161, v235
	v_pk_mul_f32 v[114:115], v[114:115], v[180:181] op_sel_hi:[1,0]
	v_pk_mul_f32 v[104:105], v[104:105], v[180:181] op_sel_hi:[1,0]
	v_cndmask_b32_e32 v161, v163, v161, vcc
	v_div_scale_f32 v163, s[0:1], v161, v161, 1.0
	v_rcp_f32_e32 v165, v163
	v_pk_mul_f32 v[102:103], v[102:103], v[180:181] op_sel_hi:[1,0]
	v_fma_f32 v167, -v163, v165, 1.0
	v_fmac_f32_e32 v165, v167, v165
	v_div_scale_f32 v167, vcc, 1.0, v161, 1.0
	v_mul_f32_e32 v169, v167, v165
	v_fma_f32 v171, -v163, v169, v167
	v_fmac_f32_e32 v169, v171, v165
	v_fma_f32 v163, -v163, v169, v167
	v_div_fmas_f32 v163, v163, v165, v169
	v_cmp_gt_f32_e32 vcc, s6, v146
	v_div_fixup_f32 v182, v163, v161, 1.0
	v_pk_mul_f32 v[98:99], v[98:99], v[182:183] op_sel_hi:[1,0]
	v_cndmask_b32_e32 v146, v146, v147, vcc
	v_sqrt_f32_e32 v147, v146
	v_pk_mul_f32 v[88:89], v[88:89], v[182:183] op_sel_hi:[1,0]
	v_pk_mul_f32 v[86:87], v[86:87], v[182:183] op_sel_hi:[1,0]
	v_add_u32_e32 v148, -1, v147
	v_fma_f32 v149, -v148, v147, v146
	v_cmp_ge_f32_e64 s[0:1], 0, v149
	v_add_u32_e32 v149, 1, v147
	s_nop 0
	v_cndmask_b32_e64 v148, v147, v148, s[0:1]
	v_fma_f32 v147, -v149, v147, v146
	v_cmp_lt_f32_e64 s[0:1], 0, v147
	s_nop 1
	v_cndmask_b32_e64 v147, v148, v149, s[0:1]
	v_mul_f32_e32 v148, 0x37800000, v147
	v_cndmask_b32_e32 v147, v147, v148, vcc
	v_cmp_class_f32_e32 vcc, v146, v235
	s_nop 1
	v_cndmask_b32_e32 v146, v147, v146, vcc
	v_div_scale_f32 v147, s[0:1], v146, v146, 1.0
	v_rcp_f32_e32 v148, v147
	s_nop 0
	v_fma_f32 v149, -v147, v148, 1.0
	v_fmac_f32_e32 v148, v149, v148
	v_div_scale_f32 v149, vcc, 1.0, v146, 1.0
	v_mul_f32_e32 v161, v149, v148
	v_fma_f32 v163, -v147, v161, v149
	v_fmac_f32_e32 v161, v163, v148
	v_fma_f32 v147, -v147, v161, v149
	v_div_fmas_f32 v147, v147, v148, v161
	v_mov_b32_e32 v148, v143
	v_mov_b32_e32 v149, v144
	v_mov_b32_e32 v143, v145
	v_pk_add_f32 v[142:143], v[148:149], v[142:143]
	v_div_fixup_f32 v146, v147, v146, 1.0
	v_add_f32_e32 v142, v142, v143
	v_fmamk_f32 v142, v142, 0x3a800000, v234
	v_cmp_gt_f32_e32 vcc, s6, v142
	v_mul_f32_e32 v143, 0x4f800000, v142
	s_nop 0
	v_cndmask_b32_e32 v142, v142, v143, vcc
	v_sqrt_f32_e32 v143, v142
	s_nop 0
	v_add_u32_e32 v144, -1, v143
	v_fma_f32 v145, -v144, v143, v142
	v_cmp_ge_f32_e64 s[0:1], 0, v145
	v_add_u32_e32 v145, 1, v143
	s_nop 0
	v_cndmask_b32_e64 v144, v143, v144, s[0:1]
	v_fma_f32 v143, -v145, v143, v142
	v_cmp_lt_f32_e64 s[0:1], 0, v143
	s_nop 1
	v_cndmask_b32_e64 v143, v144, v145, s[0:1]
	v_mul_f32_e32 v144, 0x37800000, v143
	v_cndmask_b32_e32 v143, v143, v144, vcc
	v_cmp_class_f32_e32 vcc, v142, v235
	s_nop 1
	v_cndmask_b32_e32 v142, v143, v142, vcc
	v_div_scale_f32 v143, s[0:1], v142, v142, 1.0
	v_rcp_f32_e32 v144, v143
	s_nop 0
	v_fma_f32 v145, -v143, v144, 1.0
	v_fmac_f32_e32 v144, v145, v144
	v_div_scale_f32 v145, vcc, 1.0, v142, 1.0
	v_mul_f32_e32 v147, v145, v144
	v_fma_f32 v148, -v143, v147, v145
	v_fmac_f32_e32 v147, v148, v144
	v_fma_f32 v143, -v143, v147, v145
	v_div_fmas_f32 v143, v143, v144, v147
	v_mov_b32_e32 v144, v139
	v_mov_b32_e32 v145, v140
	v_mov_b32_e32 v139, v141
	v_pk_add_f32 v[138:139], v[144:145], v[138:139]
	v_div_fixup_f32 v142, v143, v142, 1.0
	v_add_f32_e32 v138, v138, v139
	v_fmamk_f32 v138, v138, 0x3a800000, v234
	v_cmp_gt_f32_e32 vcc, s6, v138
	v_mul_f32_e32 v139, 0x4f800000, v138
	v_pk_mul_f32 v[82:83], v[82:83], v[146:147] op_sel_hi:[1,0]
	v_cndmask_b32_e32 v138, v138, v139, vcc
	v_sqrt_f32_e32 v139, v138
	v_pk_mul_f32 v[72:73], v[72:73], v[146:147] op_sel_hi:[1,0]
	v_pk_mul_f32 v[70:71], v[70:71], v[146:147] op_sel_hi:[1,0]
	v_add_u32_e32 v140, -1, v139
	v_fma_f32 v141, -v140, v139, v138
	v_cmp_ge_f32_e64 s[0:1], 0, v141
	v_add_u32_e32 v141, 1, v139
	s_nop 0
	v_cndmask_b32_e64 v140, v139, v140, s[0:1]
	v_fma_f32 v139, -v141, v139, v138
	v_cmp_lt_f32_e64 s[0:1], 0, v139
	s_nop 1
	v_cndmask_b32_e64 v139, v140, v141, s[0:1]
	v_mul_f32_e32 v140, 0x37800000, v139
	v_cndmask_b32_e32 v139, v139, v140, vcc
	v_cmp_class_f32_e32 vcc, v138, v235
	s_nop 1
	v_cndmask_b32_e32 v138, v139, v138, vcc
	v_div_scale_f32 v139, s[0:1], v138, v138, 1.0
	v_rcp_f32_e32 v140, v139
	s_nop 0
	v_fma_f32 v141, -v139, v140, 1.0
	v_fmac_f32_e32 v140, v141, v140
	v_div_scale_f32 v141, vcc, 1.0, v138, 1.0
	v_mul_f32_e32 v143, v141, v140
	v_fma_f32 v144, -v139, v143, v141
	v_fmac_f32_e32 v143, v144, v140
	v_fma_f32 v139, -v139, v143, v141
	v_div_fmas_f32 v139, v139, v140, v143
	v_mov_b32_e32 v140, v135
	v_mov_b32_e32 v141, v136
	v_mov_b32_e32 v135, v137
	v_pk_add_f32 v[134:135], v[140:141], v[134:135]
	v_div_fixup_f32 v138, v139, v138, 1.0
	v_add_f32_e32 v134, v134, v135
	v_fmamk_f32 v134, v134, 0x3a800000, v234
	v_cmp_gt_f32_e32 vcc, s6, v134
	v_mul_f32_e32 v135, 0x4f800000, v134
	v_pk_mul_f32 v[62:63], v[62:63], v[142:143] op_sel_hi:[1,0]
	v_cndmask_b32_e32 v134, v134, v135, vcc
	v_sqrt_f32_e32 v135, v134
	v_pk_mul_f32 v[60:61], v[60:61], v[142:143] op_sel_hi:[1,0]
	v_pk_mul_f32 v[54:55], v[54:55], v[142:143] op_sel_hi:[1,0]
	v_pk_mul_f32 v[52:53], v[52:53], v[142:143] op_sel_hi:[1,0]
	v_add_u32_e32 v136, -1, v135
	v_fma_f32 v137, -v136, v135, v134
	v_cmp_ge_f32_e64 s[0:1], 0, v137
	v_add_u32_e32 v137, 1, v135
	s_nop 0
	v_cndmask_b32_e64 v136, v135, v136, s[0:1]
	v_fma_f32 v135, -v137, v135, v134
	v_cmp_lt_f32_e64 s[0:1], 0, v135
	s_nop 1
	v_cndmask_b32_e64 v135, v136, v137, s[0:1]
	v_mul_f32_e32 v136, 0x37800000, v135
	v_cndmask_b32_e32 v135, v135, v136, vcc
	v_cmp_class_f32_e32 vcc, v134, v235
	s_nop 1
	v_cndmask_b32_e32 v134, v135, v134, vcc
	v_div_scale_f32 v135, s[0:1], v134, v134, 1.0
	v_rcp_f32_e32 v136, v135
	s_nop 0
	v_fma_f32 v137, -v135, v136, 1.0
	v_fmac_f32_e32 v136, v137, v136
	v_div_scale_f32 v137, vcc, 1.0, v134, 1.0
	v_mul_f32_e32 v139, v137, v136
	v_fma_f32 v140, -v135, v139, v137
	v_fmac_f32_e32 v139, v140, v136
	v_fma_f32 v135, -v135, v139, v137
	v_div_fmas_f32 v135, v135, v136, v139
	v_mov_b32_e32 v136, v131
	v_mov_b32_e32 v137, v132
	v_mov_b32_e32 v131, v133
	v_pk_add_f32 v[130:131], v[136:137], v[130:131]
	v_div_fixup_f32 v134, v135, v134, 1.0
	v_add_f32_e32 v130, v130, v131
	v_fmamk_f32 v130, v130, 0x3a800000, v234
	v_cmp_gt_f32_e32 vcc, s6, v130
	v_mul_f32_e32 v131, 0x4f800000, v130
	v_pk_mul_f32 v[140:141], v[124:125], v[178:179] op_sel_hi:[1,0]
	v_cndmask_b32_e32 v130, v130, v131, vcc
	v_sqrt_f32_e32 v131, v130
	v_pk_mul_f32 v[124:125], v[122:123], v[178:179] op_sel_hi:[1,0]
	v_cvt_pk_bf16_f32 v122, v126, v127
	v_cvt_pk_bf16_f32 v123, v128, v129
	v_add_u32_e32 v132, -1, v131
	v_fma_f32 v133, -v132, v131, v130
	v_cmp_ge_f32_e64 s[0:1], 0, v133
	v_add_u32_e32 v133, 1, v131
	v_cvt_pk_bf16_f32 v124, v124, v125
	v_cvt_pk_bf16_f32 v125, v140, v141
	v_pk_mul_f32 v[48:49], v[48:49], v[138:139] op_sel_hi:[1,0]
	v_cndmask_b32_e64 v132, v131, v132, s[0:1]
	v_fma_f32 v131, -v133, v131, v130
	v_cmp_lt_f32_e64 s[0:1], 0, v131
	v_pk_mul_f32 v[38:39], v[38:39], v[138:139] op_sel_hi:[1,0]
	v_pk_mul_f32 v[36:37], v[36:37], v[138:139] op_sel_hi:[1,0]
	v_cndmask_b32_e64 v131, v132, v133, s[0:1]
	v_mul_f32_e32 v132, 0x37800000, v131
	v_cndmask_b32_e32 v131, v131, v132, vcc
	v_cmp_class_f32_e32 vcc, v130, v235
	s_nop 1
	v_cndmask_b32_e32 v130, v131, v130, vcc
	v_div_scale_f32 v131, s[0:1], v130, v130, 1.0
	v_rcp_f32_e32 v132, v131
	s_nop 0
	v_fma_f32 v133, -v131, v132, 1.0
	v_fmac_f32_e32 v132, v133, v132
	v_div_scale_f32 v133, vcc, 1.0, v130, 1.0
	v_mul_f32_e32 v135, v133, v132
	v_fma_f32 v136, -v131, v135, v133
	v_fmac_f32_e32 v135, v136, v132
	v_fma_f32 v131, -v131, v135, v133
	v_div_fmas_f32 v131, v131, v132, v135
	v_lshl_add_u32 v132, s5, 8, v183
	v_ashrrev_i32_e32 v133, 31, v132
	v_lshl_add_u64 v[132:133], v[132:133], 1, v[176:177]
	v_mad_i64_i32 v[136:137], s[0:1], s4, v174, 0
	v_lshl_add_u64 v[136:137], v[136:137], 1, v[132:133]
	global_store_dwordx4 v[136:137], v[122:125], off sc1
	v_pk_mul_f32 v[32:33], v[32:33], v[134:135] op_sel_hi:[1,0]
	v_pk_mul_f32 v[22:23], v[22:23], v[134:135] op_sel_hi:[1,0]
	v_pk_mul_f32 v[122:123], v[112:113], v[178:179] op_sel_hi:[1,0]
	v_pk_mul_f32 v[112:113], v[110:111], v[178:179] op_sel_hi:[1,0]
	v_cvt_pk_bf16_f32 v110, v118, v119
	v_cvt_pk_bf16_f32 v111, v120, v121
	v_pk_mul_f32 v[20:21], v[20:21], v[134:135] op_sel_hi:[1,0]
	v_cvt_pk_bf16_f32 v112, v112, v113
	v_cvt_pk_bf16_f32 v113, v122, v123
	global_store_dwordx4 v[136:137], v[110:113], off offset:256 sc1
	v_div_fixup_f32 v130, v131, v130, 1.0
	v_pk_mul_f32 v[16:17], v[16:17], v[130:131] op_sel_hi:[1,0]
	v_mad_i64_i32 v[110:111], s[0:1], s4, v172, 0
	v_lshl_add_u64 v[110:111], v[110:111], 1, v[132:133]
	v_pk_mul_f32 v[112:113], v[116:117], v[180:181] op_sel_hi:[1,0]
	v_pk_mul_f32 v[116:117], v[108:109], v[180:181] op_sel_hi:[1,0]
	v_pk_mul_f32 v[108:109], v[106:107], v[180:181] op_sel_hi:[1,0]
	v_cvt_pk_bf16_f32 v106, v114, v115
	v_cvt_pk_bf16_f32 v107, v112, v113
	s_and_b64 vcc, s[52:53], exec
	v_cvt_pk_bf16_f32 v108, v108, v109
	v_cvt_pk_bf16_f32 v109, v116, v117
	global_store_dwordx4 v[110:111], v[106:109], off sc1
	v_pk_mul_f32 v[6:7], v[6:7], v[130:131] op_sel_hi:[1,0]
	v_pk_mul_f32 v[4:5], v[4:5], v[130:131] op_sel_hi:[1,0]
	v_pk_mul_f32 v[106:107], v[96:97], v[180:181] op_sel_hi:[1,0]
	v_pk_mul_f32 v[96:97], v[94:95], v[180:181] op_sel_hi:[1,0]
	v_cvt_pk_bf16_f32 v94, v102, v103
	v_cvt_pk_bf16_f32 v95, v104, v105
	s_nop 0
	v_cvt_pk_bf16_f32 v96, v96, v97
	v_cvt_pk_bf16_f32 v97, v106, v107
	global_store_dwordx4 v[110:111], v[94:97], off offset:256 sc1
	s_nop 1
	v_mad_i64_i32 v[94:95], s[0:1], s4, v170, 0
	v_lshl_add_u64 v[94:95], v[94:95], 1, v[132:133]
	v_pk_mul_f32 v[96:97], v[100:101], v[182:183] op_sel_hi:[1,0]
	v_pk_mul_f32 v[100:101], v[92:93], v[182:183] op_sel_hi:[1,0]
	v_pk_mul_f32 v[92:93], v[90:91], v[182:183] op_sel_hi:[1,0]
	v_cvt_pk_bf16_f32 v90, v98, v99
	v_cvt_pk_bf16_f32 v91, v96, v97
	s_nop 0
	v_cvt_pk_bf16_f32 v92, v92, v93
	v_cvt_pk_bf16_f32 v93, v100, v101
	global_store_dwordx4 v[94:95], v[90:93], off sc1
	s_nop 1
	v_pk_mul_f32 v[90:91], v[80:81], v[182:183] op_sel_hi:[1,0]
	v_pk_mul_f32 v[80:81], v[78:79], v[182:183] op_sel_hi:[1,0]
	v_cvt_pk_bf16_f32 v78, v86, v87
	v_cvt_pk_bf16_f32 v79, v88, v89
	s_nop 0
	v_cvt_pk_bf16_f32 v80, v80, v81
	v_cvt_pk_bf16_f32 v81, v90, v91
	global_store_dwordx4 v[94:95], v[78:81], off offset:256 sc1
	s_nop 1
	v_mad_i64_i32 v[78:79], s[0:1], s4, v168, 0
	v_lshl_add_u64 v[78:79], v[78:79], 1, v[132:133]
	v_pk_mul_f32 v[80:81], v[84:85], v[146:147] op_sel_hi:[1,0]
	v_pk_mul_f32 v[84:85], v[76:77], v[146:147] op_sel_hi:[1,0]
	v_pk_mul_f32 v[76:77], v[74:75], v[146:147] op_sel_hi:[1,0]
	v_cvt_pk_bf16_f32 v74, v82, v83
	v_cvt_pk_bf16_f32 v75, v80, v81
	s_nop 0
	v_cvt_pk_bf16_f32 v76, v76, v77
	v_cvt_pk_bf16_f32 v77, v84, v85
	global_store_dwordx4 v[78:79], v[74:77], off sc1
	s_nop 1
	v_pk_mul_f32 v[74:75], v[68:69], v[146:147] op_sel_hi:[1,0]
	v_pk_mul_f32 v[68:69], v[66:67], v[146:147] op_sel_hi:[1,0]
	v_cvt_pk_bf16_f32 v66, v70, v71
	v_cvt_pk_bf16_f32 v67, v72, v73
	s_nop 0
	v_cvt_pk_bf16_f32 v68, v68, v69
	v_cvt_pk_bf16_f32 v69, v74, v75
	global_store_dwordx4 v[78:79], v[66:69], off offset:256 sc1
	s_nop 1
	v_mad_i64_i32 v[66:67], s[0:1], s4, v166, 0
	v_lshl_add_u64 v[66:67], v[66:67], 1, v[132:133]
	v_pk_mul_f32 v[68:69], v[58:59], v[142:143] op_sel_hi:[1,0]
	v_pk_mul_f32 v[58:59], v[56:57], v[142:143] op_sel_hi:[1,0]
	v_cvt_pk_bf16_f32 v56, v60, v61
	v_cvt_pk_bf16_f32 v57, v62, v63
	s_nop 0
	v_cvt_pk_bf16_f32 v58, v58, v59
	v_cvt_pk_bf16_f32 v59, v68, v69
	global_store_dwordx4 v[66:67], v[56:59], off sc1
	s_nop 1
	v_pk_mul_f32 v[56:57], v[46:47], v[142:143] op_sel_hi:[1,0]
	v_pk_mul_f32 v[46:47], v[44:45], v[142:143] op_sel_hi:[1,0]
	v_cvt_pk_bf16_f32 v44, v52, v53
	v_cvt_pk_bf16_f32 v45, v54, v55
	s_nop 0
	v_cvt_pk_bf16_f32 v46, v46, v47
	v_cvt_pk_bf16_f32 v47, v56, v57
	global_store_dwordx4 v[66:67], v[44:47], off offset:256 sc1
	s_nop 1
	v_mad_i64_i32 v[44:45], s[0:1], s4, v164, 0
	v_lshl_add_u64 v[44:45], v[44:45], 1, v[132:133]
	v_pk_mul_f32 v[46:47], v[50:51], v[138:139] op_sel_hi:[1,0]
	v_pk_mul_f32 v[50:51], v[42:43], v[138:139] op_sel_hi:[1,0]
	v_pk_mul_f32 v[42:43], v[40:41], v[138:139] op_sel_hi:[1,0]
	v_cvt_pk_bf16_f32 v40, v48, v49
	v_cvt_pk_bf16_f32 v41, v46, v47
	s_nop 0
	v_cvt_pk_bf16_f32 v42, v42, v43
	v_cvt_pk_bf16_f32 v43, v50, v51
	global_store_dwordx4 v[44:45], v[40:43], off sc1
	s_nop 1
	v_pk_mul_f32 v[40:41], v[30:31], v[138:139] op_sel_hi:[1,0]
	v_pk_mul_f32 v[30:31], v[28:29], v[138:139] op_sel_hi:[1,0]
	v_cvt_pk_bf16_f32 v28, v36, v37
	v_cvt_pk_bf16_f32 v29, v38, v39
	s_nop 0
	v_cvt_pk_bf16_f32 v30, v30, v31
	v_cvt_pk_bf16_f32 v31, v40, v41
	global_store_dwordx4 v[44:45], v[28:31], off offset:256 sc1
	s_nop 1
	v_mad_i64_i32 v[28:29], s[0:1], s4, v162, 0
	v_lshl_add_u64 v[28:29], v[28:29], 1, v[132:133]
	v_pk_mul_f32 v[30:31], v[34:35], v[134:135] op_sel_hi:[1,0]
	v_pk_mul_f32 v[34:35], v[26:27], v[134:135] op_sel_hi:[1,0]
	v_pk_mul_f32 v[26:27], v[24:25], v[134:135] op_sel_hi:[1,0]
	v_cvt_pk_bf16_f32 v24, v32, v33
	v_cvt_pk_bf16_f32 v25, v30, v31
	s_nop 0
	v_cvt_pk_bf16_f32 v26, v26, v27
	v_cvt_pk_bf16_f32 v27, v34, v35
	global_store_dwordx4 v[28:29], v[24:27], off sc1
	s_nop 1
	v_pk_mul_f32 v[24:25], v[14:15], v[134:135] op_sel_hi:[1,0]
	v_pk_mul_f32 v[14:15], v[12:13], v[134:135] op_sel_hi:[1,0]
	v_cvt_pk_bf16_f32 v12, v20, v21
	v_cvt_pk_bf16_f32 v13, v22, v23
	s_nop 0
	v_cvt_pk_bf16_f32 v14, v14, v15
	v_cvt_pk_bf16_f32 v15, v24, v25
	global_store_dwordx4 v[28:29], v[12:15], off offset:256 sc1
	s_nop 1
	v_mad_i64_i32 v[12:13], s[0:1], s4, v160, 0
	v_lshl_add_u64 v[12:13], v[12:13], 1, v[132:133]
	v_pk_mul_f32 v[14:15], v[18:19], v[130:131] op_sel_hi:[1,0]
	v_pk_mul_f32 v[18:19], v[10:11], v[130:131] op_sel_hi:[1,0]
	v_pk_mul_f32 v[10:11], v[8:9], v[130:131] op_sel_hi:[1,0]
	v_cvt_pk_bf16_f32 v8, v16, v17
	v_cvt_pk_bf16_f32 v9, v14, v15
	s_nop 0
	v_cvt_pk_bf16_f32 v10, v10, v11
	v_cvt_pk_bf16_f32 v11, v18, v19
	global_store_dwordx4 v[12:13], v[8:11], off sc1
	s_nop 1
	v_pk_mul_f32 v[8:9], v[2:3], v[130:131] op_sel_hi:[1,0]
	v_pk_mul_f32 v[2:3], v[0:1], v[130:131] op_sel_hi:[1,0]
	v_cvt_pk_bf16_f32 v0, v4, v5
	v_cvt_pk_bf16_f32 v1, v6, v7
	s_nop 0
	v_cvt_pk_bf16_f32 v2, v2, v3
	v_cvt_pk_bf16_f32 v3, v8, v9
	global_store_dwordx4 v[12:13], v[0:3], off offset:256 sc1
	s_cbranch_vccnz .LBB0_805
	s_add_i32 s57, s57, 1
	s_cmp_lg_u32 s57, s24
	s_cbranch_scc1 .LBB0_805
	s_waitcnt vmcnt(0)
	v_mbcnt_lo_u32_b32 v1, -1, 0
	v_mbcnt_hi_u32_b32 v1, -1, v1
	v_mov_b32_e32 v0, 0
	v_cmp_eq_u32_e32 vcc, 0, v1
	s_and_saveexec_b64 s[28:29], vcc
	s_cbranch_execz .LBB0_798
	s_mov_b64 s[52:53], exec
	v_mbcnt_lo_u32_b32 v0, s52, 0
	v_mbcnt_hi_u32_b32 v0, s53, v0
	v_cmp_eq_u32_e64 s[0:1], 0, v0
	s_and_saveexec_b64 s[36:37], s[0:1]
	s_bcnt1_i32_b64 s0, s[52:53]
	v_mov_b32_e32 v1, s27
	v_mov_b32_e32 v2, s0
	ds_add_rtn_u32 v1, v1, v2
	s_or_b64 exec, exec, s[36:37]
	s_waitcnt lgkmcnt(0)
	v_readfirstlane_b32 s0, v1
	s_nop 1
	v_add_u32_e32 v0, s0, v0
